# NSA sliding-window branch loop hand-written (fixed register allocation, no loop-carried copies, SGPR-base loads, next-K prefetched in place) on top of item-loop in-place prefetch
# speedup vs baseline: 1.0038x; 1.0038x over previous
.LBB0_1258:
	s_mov_b64 s[18:19], s[4:5]
	v_mov_b64_e32 v[34:35], v[16:17]
	v_mov_b64_e32 v[36:37], v[16:17]
	v_mov_b64_e32 v[38:39], v[16:17]
	v_mov_b64_e32 v[40:41], v[16:17]
	v_mov_b64_e32 v[42:43], v[16:17]
	v_mov_b64_e32 v[44:45], v[16:17]
	v_mov_b64_e32 v[46:47], v[16:17]
	v_mov_b64_e32 v[48:49], v[16:17]
	v_mov_b64_e32 v[50:51], v[16:17]
	v_mov_b64_e32 v[52:53], v[16:17]
	v_mov_b64_e32 v[54:55], v[16:17]
	v_mov_b64_e32 v[56:57], v[16:17]
	v_mov_b64_e32 v[58:59], v[16:17]
	v_mov_b64_e32 v[60:61], v[16:17]
	v_mov_b64_e32 v[62:63], v[16:17]
	v_mov_b64_e32 v[64:65], v[16:17]
	v_mov_b32_e32 v66, 0
.Lw_loop:
	s_add_u32 s20, s18, 0x800000
	s_addc_u32 s21, s19, 0
	global_load_dwordx4 v[130:133], v194, s[20:21]
	global_load_dwordx4 v[146:149], v200, s[20:21]
	global_load_dwordx4 v[134:137], v194, s[20:21] offset:1024
	global_load_dwordx4 v[150:153], v202, s[20:21]
	global_load_dwordx4 v[138:141], v194, s[20:21] offset:2048
	global_load_dwordx4 v[154:157], v204, s[20:21]
	global_load_dwordx4 v[142:145], v194, s[20:21] offset:3072
	global_load_dwordx4 v[158:161], v206, s[20:21]
	ds_read_b128 v[68:71], v224
	ds_read_b128 v[72:75], v224 offset:32
	ds_read_b128 v[76:79], v224 offset:64
	ds_read_b128 v[80:83], v224 offset:96
	s_cmp_lt_i32 s17, s96
	s_cbranch_scc0 .Lw_near
	s_cmp_eq_u32 s17, s15
	s_cbranch_scc1 .Lw_band
	s_waitcnt vmcnt(8) lgkmcnt(3)
	v_mfma_f32_32x32x16_bf16 v[162:177], v[98:101], v[68:71], 0
	v_mfma_f32_32x32x16_bf16 v[178:193], v[114:117], v[68:71], 0
	s_waitcnt lgkmcnt(2)
	v_mfma_f32_32x32x16_bf16 v[162:177], v[102:105], v[72:75], v[162:177]
	v_mfma_f32_32x32x16_bf16 v[178:193], v[118:121], v[72:75], v[178:193]
	s_waitcnt lgkmcnt(1)
	v_mfma_f32_32x32x16_bf16 v[162:177], v[106:109], v[76:79], v[162:177]
	v_mfma_f32_32x32x16_bf16 v[178:193], v[122:125], v[76:79], v[178:193]
	s_waitcnt lgkmcnt(0)
	v_mfma_f32_32x32x16_bf16 v[162:177], v[110:113], v[80:83], v[162:177]
	v_mfma_f32_32x32x16_bf16 v[178:193], v[126:129], v[80:83], v[178:193]
	s_add_u32 s22, s18, 0x2000
	s_addc_u32 s23, s19, 0
	global_load_dwordx4 v[98:101], v194, s[22:23]
	global_load_dwordx4 v[102:105], v194, s[22:23] offset:1024
	global_load_dwordx4 v[106:109], v194, s[22:23] offset:2048
	global_load_dwordx4 v[110:113], v194, s[22:23] offset:3072
	global_load_dwordx4 v[114:117], v200, s[22:23]
	global_load_dwordx4 v[118:121], v202, s[22:23]
	global_load_dwordx4 v[122:125], v204, s[22:23]
	global_load_dwordx4 v[126:129], v206, s[22:23]
	s_nop 1
	v_max3_f32 v92, v162, v163, v164
	v_max3_f32 v92, v92, v165, v166
	v_max3_f32 v92, v92, v167, v168
	v_max3_f32 v92, v92, v169, v170
	v_max3_f32 v92, v92, v171, v172
	v_max3_f32 v92, v92, v173, v174
	v_max3_f32 v92, v92, v175, v176
	v_max3_f32 v92, v92, v177, v177
	v_max3_f32 v96, v178, v179, v180
	v_max3_f32 v96, v96, v181, v182
	v_max3_f32 v96, v96, v183, v184
	v_max3_f32 v96, v96, v185, v186
	v_max3_f32 v96, v96, v187, v188
	v_max3_f32 v96, v96, v189, v190
	v_max3_f32 v96, v96, v191, v192
	v_max3_f32 v96, v96, v193, v193
	v_max_f32_e32 v92, v92, v96
	v_fmamk_f32 v92, v92, 0x3fb8aa3b, v208
	v_mov_b32_e32 v93, v92
	s_nop 1
	v_permlane32_swap_b32_e32 v92, v93
	v_max3_f32 v96, v234, v92, v93
	v_cmp_neq_f32_e32 vcc, s68, v96
	s_nop 1
	v_cndmask_b32_e32 v94, 0, v96, vcc
	v_cmp_neq_f32_e32 vcc, v96, v234
	s_cbranch_vccz .Lw_nr_far
	v_sub_f32_e32 v97, v234, v94
	v_exp_f32_e32 v97, v97
	s_nop 0
	v_mul_f32_e32 v34, v97, v34
	v_mul_f32_e32 v35, v97, v35
	v_mul_f32_e32 v36, v97, v36
	v_mul_f32_e32 v37, v97, v37
	v_mul_f32_e32 v38, v97, v38
	v_mul_f32_e32 v39, v97, v39
	v_mul_f32_e32 v40, v97, v40
	v_mul_f32_e32 v41, v97, v41
	v_mul_f32_e32 v42, v97, v42
	v_mul_f32_e32 v43, v97, v43
	v_mul_f32_e32 v44, v97, v44
	v_mul_f32_e32 v45, v97, v45
	v_mul_f32_e32 v46, v97, v46
	v_mul_f32_e32 v47, v97, v47
	v_mul_f32_e32 v48, v97, v48
	v_mul_f32_e32 v49, v97, v49
	v_mul_f32_e32 v50, v97, v50
	v_mul_f32_e32 v51, v97, v51
	v_mul_f32_e32 v52, v97, v52
	v_mul_f32_e32 v53, v97, v53
	v_mul_f32_e32 v54, v97, v54
	v_mul_f32_e32 v55, v97, v55
	v_mul_f32_e32 v56, v97, v56
	v_mul_f32_e32 v57, v97, v57
	v_mul_f32_e32 v58, v97, v58
	v_mul_f32_e32 v59, v97, v59
	v_mul_f32_e32 v60, v97, v60
	v_mul_f32_e32 v61, v97, v61
	v_mul_f32_e32 v62, v97, v62
	v_mul_f32_e32 v63, v97, v63
	v_mul_f32_e32 v64, v97, v64
	v_mul_f32_e32 v65, v97, v65
	v_mul_f32_e32 v66, v97, v66
.Lw_nr_far:
	v_mov_b32_e32 v234, v96
	v_sub_f32_e32 v95, v208, v94
	v_fmamk_f32 v162, v162, 0x3fb8aa3b, v95
	v_fmamk_f32 v163, v163, 0x3fb8aa3b, v95
	v_fmamk_f32 v164, v164, 0x3fb8aa3b, v95
	v_fmamk_f32 v165, v165, 0x3fb8aa3b, v95
	v_fmamk_f32 v166, v166, 0x3fb8aa3b, v95
	v_fmamk_f32 v167, v167, 0x3fb8aa3b, v95
	v_fmamk_f32 v168, v168, 0x3fb8aa3b, v95
	v_fmamk_f32 v169, v169, 0x3fb8aa3b, v95
	v_exp_f32_e32 v162, v162
	v_exp_f32_e32 v163, v163
	v_exp_f32_e32 v164, v164
	v_exp_f32_e32 v165, v165
	v_exp_f32_e32 v166, v166
	v_exp_f32_e32 v167, v167
	v_exp_f32_e32 v168, v168
	v_exp_f32_e32 v169, v169
	v_add_f32_e32 v235, v162, v163
	v_add_f32_e32 v235, v235, v164
	v_add_f32_e32 v235, v235, v165
	v_add_f32_e32 v235, v235, v166
	v_add_f32_e32 v235, v235, v167
	v_add_f32_e32 v235, v235, v168
	v_add_f32_e32 v235, v235, v169
	v_cvt_pk_bf16_f32 v84, v162, v163
	v_cvt_pk_bf16_f32 v85, v164, v165
	v_cvt_pk_bf16_f32 v86, v166, v167
	v_cvt_pk_bf16_f32 v87, v168, v169
	v_fmamk_f32 v170, v170, 0x3fb8aa3b, v95
	v_fmamk_f32 v171, v171, 0x3fb8aa3b, v95
	v_fmamk_f32 v172, v172, 0x3fb8aa3b, v95
	v_fmamk_f32 v173, v173, 0x3fb8aa3b, v95
	v_fmamk_f32 v174, v174, 0x3fb8aa3b, v95
	v_fmamk_f32 v175, v175, 0x3fb8aa3b, v95
	v_fmamk_f32 v176, v176, 0x3fb8aa3b, v95
	v_fmamk_f32 v177, v177, 0x3fb8aa3b, v95
	s_waitcnt vmcnt(8)
	v_mfma_f32_32x32x16_bf16 v[34:49], v[130:133], v[84:87], v[34:49]
	v_mfma_f32_32x32x16_bf16 v[50:65], v[146:149], v[84:87], v[50:65]
	v_exp_f32_e32 v170, v170
	v_exp_f32_e32 v171, v171
	v_exp_f32_e32 v172, v172
	v_exp_f32_e32 v173, v173
	v_exp_f32_e32 v174, v174
	v_exp_f32_e32 v175, v175
	v_exp_f32_e32 v176, v176
	v_exp_f32_e32 v177, v177
	v_add_f32_e32 v236, v170, v171
	v_add_f32_e32 v236, v236, v172
	v_add_f32_e32 v236, v236, v173
	v_add_f32_e32 v236, v236, v174
	v_add_f32_e32 v236, v236, v175
	v_add_f32_e32 v236, v236, v176
	v_add_f32_e32 v236, v236, v177
	v_cvt_pk_bf16_f32 v88, v170, v171
	v_cvt_pk_bf16_f32 v89, v172, v173
	v_cvt_pk_bf16_f32 v90, v174, v175
	v_cvt_pk_bf16_f32 v91, v176, v177
	v_fmamk_f32 v178, v178, 0x3fb8aa3b, v95
	v_fmamk_f32 v179, v179, 0x3fb8aa3b, v95
	v_fmamk_f32 v180, v180, 0x3fb8aa3b, v95
	v_fmamk_f32 v181, v181, 0x3fb8aa3b, v95
	v_fmamk_f32 v182, v182, 0x3fb8aa3b, v95
	v_fmamk_f32 v183, v183, 0x3fb8aa3b, v95
	v_fmamk_f32 v184, v184, 0x3fb8aa3b, v95
	v_fmamk_f32 v185, v185, 0x3fb8aa3b, v95
	v_mfma_f32_32x32x16_bf16 v[34:49], v[134:137], v[88:91], v[34:49]
	v_mfma_f32_32x32x16_bf16 v[50:65], v[150:153], v[88:91], v[50:65]
	v_exp_f32_e32 v178, v178
	v_exp_f32_e32 v179, v179
	v_exp_f32_e32 v180, v180
	v_exp_f32_e32 v181, v181
	v_exp_f32_e32 v182, v182
	v_exp_f32_e32 v183, v183
	v_exp_f32_e32 v184, v184
	v_exp_f32_e32 v185, v185
	v_add_f32_e32 v237, v178, v179
	v_add_f32_e32 v237, v237, v180
	v_add_f32_e32 v237, v237, v181
	v_add_f32_e32 v237, v237, v182
	v_add_f32_e32 v237, v237, v183
	v_add_f32_e32 v237, v237, v184
	v_add_f32_e32 v237, v237, v185
	v_cvt_pk_bf16_f32 v84, v178, v179
	v_cvt_pk_bf16_f32 v85, v180, v181
	v_cvt_pk_bf16_f32 v86, v182, v183
	v_cvt_pk_bf16_f32 v87, v184, v185
	v_fmamk_f32 v186, v186, 0x3fb8aa3b, v95
	v_fmamk_f32 v187, v187, 0x3fb8aa3b, v95
	v_fmamk_f32 v188, v188, 0x3fb8aa3b, v95
	v_fmamk_f32 v189, v189, 0x3fb8aa3b, v95
	v_fmamk_f32 v190, v190, 0x3fb8aa3b, v95
	v_fmamk_f32 v191, v191, 0x3fb8aa3b, v95
	v_fmamk_f32 v192, v192, 0x3fb8aa3b, v95
	v_fmamk_f32 v193, v193, 0x3fb8aa3b, v95
	v_mfma_f32_32x32x16_bf16 v[34:49], v[138:141], v[84:87], v[34:49]
	v_mfma_f32_32x32x16_bf16 v[50:65], v[154:157], v[84:87], v[50:65]
	v_exp_f32_e32 v186, v186
	v_exp_f32_e32 v187, v187
	v_exp_f32_e32 v188, v188
	v_exp_f32_e32 v189, v189
	v_exp_f32_e32 v190, v190
	v_exp_f32_e32 v191, v191
	v_exp_f32_e32 v192, v192
	v_exp_f32_e32 v193, v193
	v_add_f32_e32 v238, v186, v187
	v_add_f32_e32 v238, v238, v188
	v_add_f32_e32 v238, v238, v189
	v_add_f32_e32 v238, v238, v190
	v_add_f32_e32 v238, v238, v191
	v_add_f32_e32 v238, v238, v192
	v_add_f32_e32 v238, v238, v193
	v_cvt_pk_bf16_f32 v88, v186, v187
	v_cvt_pk_bf16_f32 v89, v188, v189
	v_cvt_pk_bf16_f32 v90, v190, v191
	v_cvt_pk_bf16_f32 v91, v192, v193
	s_nop 1
	v_mfma_f32_32x32x16_bf16 v[34:49], v[142:145], v[88:91], v[34:49]
	v_mfma_f32_32x32x16_bf16 v[50:65], v[158:161], v[88:91], v[50:65]
	v_add_f32_e32 v235, v235, v236
	v_add_f32_e32 v237, v237, v238
	v_add_f32_e32 v235, v235, v237
	v_add_f32_e32 v66, v66, v235
	s_branch .Lw_next
.Lw_band:
	s_waitcnt vmcnt(8) lgkmcnt(3)
	v_mfma_f32_32x32x16_bf16 v[162:177], v[98:101], v[68:71], 0
	v_mfma_f32_32x32x16_bf16 v[178:193], v[114:117], v[68:71], 0
	s_waitcnt lgkmcnt(2)
	v_mfma_f32_32x32x16_bf16 v[162:177], v[102:105], v[72:75], v[162:177]
	v_mfma_f32_32x32x16_bf16 v[178:193], v[118:121], v[72:75], v[178:193]
	s_waitcnt lgkmcnt(1)
	v_mfma_f32_32x32x16_bf16 v[162:177], v[106:109], v[76:79], v[162:177]
	v_mfma_f32_32x32x16_bf16 v[178:193], v[122:125], v[76:79], v[178:193]
	s_waitcnt lgkmcnt(0)
	v_mfma_f32_32x32x16_bf16 v[162:177], v[110:113], v[80:83], v[162:177]
	v_mfma_f32_32x32x16_bf16 v[178:193], v[126:129], v[80:83], v[178:193]
	s_add_u32 s22, s18, 0x2000
	s_addc_u32 s23, s19, 0
	global_load_dwordx4 v[98:101], v194, s[22:23]
	global_load_dwordx4 v[102:105], v194, s[22:23] offset:1024
	global_load_dwordx4 v[106:109], v194, s[22:23] offset:2048
	global_load_dwordx4 v[110:113], v194, s[22:23] offset:3072
	global_load_dwordx4 v[114:117], v200, s[22:23]
	global_load_dwordx4 v[118:121], v202, s[22:23]
	global_load_dwordx4 v[122:125], v204, s[22:23]
	global_load_dwordx4 v[126:129], v206, s[22:23]
	v_sub_u32_e32 v239, v211, v226
	s_nop 0
	v_fmamk_f32 v162, v162, 0x3fb8aa3b, v208
	v_cmp_gt_u32_e32 vcc, 512, v239
	s_nop 1
	v_cndmask_b32_e32 v162, v219, v162, vcc
	v_fmamk_f32 v163, v163, 0x3fb8aa3b, v208
	v_cmp_gt_u32_e32 vcc, 513, v239
	s_nop 1
	v_cndmask_b32_e32 v163, v219, v163, vcc
	v_fmamk_f32 v164, v164, 0x3fb8aa3b, v208
	v_cmp_gt_u32_e32 vcc, 514, v239
	s_nop 1
	v_cndmask_b32_e32 v164, v219, v164, vcc
	v_fmamk_f32 v165, v165, 0x3fb8aa3b, v208
	v_cmp_gt_u32_e32 vcc, 515, v239
	s_nop 1
	v_cndmask_b32_e32 v165, v219, v165, vcc
	v_fmamk_f32 v166, v166, 0x3fb8aa3b, v208
	v_cmp_gt_u32_e32 vcc, 520, v239
	s_nop 1
	v_cndmask_b32_e32 v166, v219, v166, vcc
	v_fmamk_f32 v167, v167, 0x3fb8aa3b, v208
	v_cmp_gt_u32_e32 vcc, 521, v239
	s_nop 1
	v_cndmask_b32_e32 v167, v219, v167, vcc
	v_fmamk_f32 v168, v168, 0x3fb8aa3b, v208
	v_cmp_gt_u32_e32 vcc, 522, v239
	s_nop 1
	v_cndmask_b32_e32 v168, v219, v168, vcc
	v_fmamk_f32 v169, v169, 0x3fb8aa3b, v208
	v_cmp_gt_u32_e32 vcc, 523, v239
	s_nop 1
	v_cndmask_b32_e32 v169, v219, v169, vcc
	v_fmamk_f32 v170, v170, 0x3fb8aa3b, v208
	v_cmp_gt_u32_e32 vcc, 528, v239
	s_nop 1
	v_cndmask_b32_e32 v170, v219, v170, vcc
	v_fmamk_f32 v171, v171, 0x3fb8aa3b, v208
	v_cmp_gt_u32_e32 vcc, 529, v239
	s_nop 1
	v_cndmask_b32_e32 v171, v219, v171, vcc
	v_fmamk_f32 v172, v172, 0x3fb8aa3b, v208
	v_cmp_gt_u32_e32 vcc, 530, v239
	s_nop 1
	v_cndmask_b32_e32 v172, v219, v172, vcc
	v_fmamk_f32 v173, v173, 0x3fb8aa3b, v208
	v_cmp_gt_u32_e32 vcc, 531, v239
	s_nop 1
	v_cndmask_b32_e32 v173, v219, v173, vcc
	v_fmamk_f32 v174, v174, 0x3fb8aa3b, v208
	v_cmp_gt_u32_e32 vcc, 536, v239
	s_nop 1
	v_cndmask_b32_e32 v174, v219, v174, vcc
	v_fmamk_f32 v175, v175, 0x3fb8aa3b, v208
	v_cmp_gt_u32_e32 vcc, 537, v239
	s_nop 1
	v_cndmask_b32_e32 v175, v219, v175, vcc
	v_fmamk_f32 v176, v176, 0x3fb8aa3b, v208
	v_cmp_gt_u32_e32 vcc, 538, v239
	s_nop 1
	v_cndmask_b32_e32 v176, v219, v176, vcc
	v_fmamk_f32 v177, v177, 0x3fb8aa3b, v208
	v_cmp_gt_u32_e32 vcc, 539, v239
	s_nop 1
	v_cndmask_b32_e32 v177, v219, v177, vcc
	v_fmamk_f32 v178, v178, 0x3fb8aa3b, v208
	v_cmp_gt_u32_e32 vcc, 544, v239
	s_nop 1
	v_cndmask_b32_e32 v178, v219, v178, vcc
	v_fmamk_f32 v179, v179, 0x3fb8aa3b, v208
	v_cmp_gt_u32_e32 vcc, 545, v239
	s_nop 1
	v_cndmask_b32_e32 v179, v219, v179, vcc
	v_fmamk_f32 v180, v180, 0x3fb8aa3b, v208
	v_cmp_gt_u32_e32 vcc, 546, v239
	s_nop 1
	v_cndmask_b32_e32 v180, v219, v180, vcc
	v_fmamk_f32 v181, v181, 0x3fb8aa3b, v208
	v_cmp_gt_u32_e32 vcc, 547, v239
	s_nop 1
	v_cndmask_b32_e32 v181, v219, v181, vcc
	v_fmamk_f32 v182, v182, 0x3fb8aa3b, v208
	v_cmp_gt_u32_e32 vcc, 552, v239
	s_nop 1
	v_cndmask_b32_e32 v182, v219, v182, vcc
	v_fmamk_f32 v183, v183, 0x3fb8aa3b, v208
	v_cmp_gt_u32_e32 vcc, 553, v239
	s_nop 1
	v_cndmask_b32_e32 v183, v219, v183, vcc
	v_fmamk_f32 v184, v184, 0x3fb8aa3b, v208
	v_cmp_gt_u32_e32 vcc, 554, v239
	s_nop 1
	v_cndmask_b32_e32 v184, v219, v184, vcc
	v_fmamk_f32 v185, v185, 0x3fb8aa3b, v208
	v_cmp_gt_u32_e32 vcc, 555, v239
	s_nop 1
	v_cndmask_b32_e32 v185, v219, v185, vcc
	v_fmamk_f32 v186, v186, 0x3fb8aa3b, v208
	v_cmp_gt_u32_e32 vcc, 560, v239
	s_nop 1
	v_cndmask_b32_e32 v186, v219, v186, vcc
	v_fmamk_f32 v187, v187, 0x3fb8aa3b, v208
	v_cmp_gt_u32_e32 vcc, 561, v239
	s_nop 1
	v_cndmask_b32_e32 v187, v219, v187, vcc
	v_fmamk_f32 v188, v188, 0x3fb8aa3b, v208
	v_cmp_gt_u32_e32 vcc, 562, v239
	s_nop 1
	v_cndmask_b32_e32 v188, v219, v188, vcc
	v_fmamk_f32 v189, v189, 0x3fb8aa3b, v208
	v_cmp_gt_u32_e32 vcc, 563, v239
	s_nop 1
	v_cndmask_b32_e32 v189, v219, v189, vcc
	v_fmamk_f32 v190, v190, 0x3fb8aa3b, v208
	v_cmp_gt_u32_e32 vcc, 568, v239
	s_nop 1
	v_cndmask_b32_e32 v190, v219, v190, vcc
	v_fmamk_f32 v191, v191, 0x3fb8aa3b, v208
	v_cmp_gt_u32_e32 vcc, 569, v239
	s_nop 1
	v_cndmask_b32_e32 v191, v219, v191, vcc
	v_fmamk_f32 v192, v192, 0x3fb8aa3b, v208
	v_cmp_gt_u32_e32 vcc, 570, v239
	s_nop 1
	v_cndmask_b32_e32 v192, v219, v192, vcc
	v_fmamk_f32 v193, v193, 0x3fb8aa3b, v208
	v_cmp_gt_u32_e32 vcc, 571, v239
	s_nop 1
	v_cndmask_b32_e32 v193, v219, v193, vcc
	v_max3_f32 v92, v162, v163, v164
	v_max3_f32 v92, v92, v165, v166
	v_max3_f32 v92, v92, v167, v168
	v_max3_f32 v92, v92, v169, v170
	v_max3_f32 v92, v92, v171, v172
	v_max3_f32 v92, v92, v173, v174
	v_max3_f32 v92, v92, v175, v176
	v_max3_f32 v92, v92, v177, v177
	v_max3_f32 v96, v178, v179, v180
	v_max3_f32 v96, v96, v181, v182
	v_max3_f32 v96, v96, v183, v184
	v_max3_f32 v96, v96, v185, v186
	v_max3_f32 v96, v96, v187, v188
	v_max3_f32 v96, v96, v189, v190
	v_max3_f32 v96, v96, v191, v192
	v_max3_f32 v96, v96, v193, v193
	v_max_f32_e32 v92, v92, v96
	v_mov_b32_e32 v93, v92
	s_nop 1
	v_permlane32_swap_b32_e32 v92, v93
	v_max3_f32 v96, v234, v92, v93
	v_cmp_neq_f32_e32 vcc, s68, v96
	s_nop 1
	v_cndmask_b32_e32 v94, 0, v96, vcc
	v_cmp_neq_f32_e32 vcc, v96, v234
	s_cbranch_vccz .Lw_nr_band
	v_sub_f32_e32 v97, v234, v94
	v_exp_f32_e32 v97, v97
	s_nop 0
	v_mul_f32_e32 v34, v97, v34
	v_mul_f32_e32 v35, v97, v35
	v_mul_f32_e32 v36, v97, v36
	v_mul_f32_e32 v37, v97, v37
	v_mul_f32_e32 v38, v97, v38
	v_mul_f32_e32 v39, v97, v39
	v_mul_f32_e32 v40, v97, v40
	v_mul_f32_e32 v41, v97, v41
	v_mul_f32_e32 v42, v97, v42
	v_mul_f32_e32 v43, v97, v43
	v_mul_f32_e32 v44, v97, v44
	v_mul_f32_e32 v45, v97, v45
	v_mul_f32_e32 v46, v97, v46
	v_mul_f32_e32 v47, v97, v47
	v_mul_f32_e32 v48, v97, v48
	v_mul_f32_e32 v49, v97, v49
	v_mul_f32_e32 v50, v97, v50
	v_mul_f32_e32 v51, v97, v51
	v_mul_f32_e32 v52, v97, v52
	v_mul_f32_e32 v53, v97, v53
	v_mul_f32_e32 v54, v97, v54
	v_mul_f32_e32 v55, v97, v55
	v_mul_f32_e32 v56, v97, v56
	v_mul_f32_e32 v57, v97, v57
	v_mul_f32_e32 v58, v97, v58
	v_mul_f32_e32 v59, v97, v59
	v_mul_f32_e32 v60, v97, v60
	v_mul_f32_e32 v61, v97, v61
	v_mul_f32_e32 v62, v97, v62
	v_mul_f32_e32 v63, v97, v63
	v_mul_f32_e32 v64, v97, v64
	v_mul_f32_e32 v65, v97, v65
	v_mul_f32_e32 v66, v97, v66
.Lw_nr_band:
	v_mov_b32_e32 v234, v96
	v_sub_f32_e32 v162, v162, v94
	v_sub_f32_e32 v163, v163, v94
	v_sub_f32_e32 v164, v164, v94
	v_sub_f32_e32 v165, v165, v94
	v_sub_f32_e32 v166, v166, v94
	v_sub_f32_e32 v167, v167, v94
	v_sub_f32_e32 v168, v168, v94
	v_sub_f32_e32 v169, v169, v94
	v_exp_f32_e32 v162, v162
	v_exp_f32_e32 v163, v163
	v_exp_f32_e32 v164, v164
	v_exp_f32_e32 v165, v165
	v_exp_f32_e32 v166, v166
	v_exp_f32_e32 v167, v167
	v_exp_f32_e32 v168, v168
	v_exp_f32_e32 v169, v169
	v_add_f32_e32 v235, v162, v163
	v_add_f32_e32 v235, v235, v164
	v_add_f32_e32 v235, v235, v165
	v_add_f32_e32 v235, v235, v166
	v_add_f32_e32 v235, v235, v167
	v_add_f32_e32 v235, v235, v168
	v_add_f32_e32 v235, v235, v169
	v_cvt_pk_bf16_f32 v84, v162, v163
	v_cvt_pk_bf16_f32 v85, v164, v165
	v_cvt_pk_bf16_f32 v86, v166, v167
	v_cvt_pk_bf16_f32 v87, v168, v169
	v_sub_f32_e32 v170, v170, v94
	v_sub_f32_e32 v171, v171, v94
	v_sub_f32_e32 v172, v172, v94
	v_sub_f32_e32 v173, v173, v94
	v_sub_f32_e32 v174, v174, v94
	v_sub_f32_e32 v175, v175, v94
	v_sub_f32_e32 v176, v176, v94
	v_sub_f32_e32 v177, v177, v94
	s_waitcnt vmcnt(8)
	v_mfma_f32_32x32x16_bf16 v[34:49], v[130:133], v[84:87], v[34:49]
	v_mfma_f32_32x32x16_bf16 v[50:65], v[146:149], v[84:87], v[50:65]
	v_exp_f32_e32 v170, v170
	v_exp_f32_e32 v171, v171
	v_exp_f32_e32 v172, v172
	v_exp_f32_e32 v173, v173
	v_exp_f32_e32 v174, v174
	v_exp_f32_e32 v175, v175
	v_exp_f32_e32 v176, v176
	v_exp_f32_e32 v177, v177
	v_add_f32_e32 v236, v170, v171
	v_add_f32_e32 v236, v236, v172
	v_add_f32_e32 v236, v236, v173
	v_add_f32_e32 v236, v236, v174
	v_add_f32_e32 v236, v236, v175
	v_add_f32_e32 v236, v236, v176
	v_add_f32_e32 v236, v236, v177
	v_cvt_pk_bf16_f32 v88, v170, v171
	v_cvt_pk_bf16_f32 v89, v172, v173
	v_cvt_pk_bf16_f32 v90, v174, v175
	v_cvt_pk_bf16_f32 v91, v176, v177
	v_sub_f32_e32 v178, v178, v94
	v_sub_f32_e32 v179, v179, v94
	v_sub_f32_e32 v180, v180, v94
	v_sub_f32_e32 v181, v181, v94
	v_sub_f32_e32 v182, v182, v94
	v_sub_f32_e32 v183, v183, v94
	v_sub_f32_e32 v184, v184, v94
	v_sub_f32_e32 v185, v185, v94
	v_mfma_f32_32x32x16_bf16 v[34:49], v[134:137], v[88:91], v[34:49]
	v_mfma_f32_32x32x16_bf16 v[50:65], v[150:153], v[88:91], v[50:65]
	v_exp_f32_e32 v178, v178
	v_exp_f32_e32 v179, v179
	v_exp_f32_e32 v180, v180
	v_exp_f32_e32 v181, v181
	v_exp_f32_e32 v182, v182
	v_exp_f32_e32 v183, v183
	v_exp_f32_e32 v184, v184
	v_exp_f32_e32 v185, v185
	v_add_f32_e32 v237, v178, v179
	v_add_f32_e32 v237, v237, v180
	v_add_f32_e32 v237, v237, v181
	v_add_f32_e32 v237, v237, v182
	v_add_f32_e32 v237, v237, v183
	v_add_f32_e32 v237, v237, v184
	v_add_f32_e32 v237, v237, v185
	v_cvt_pk_bf16_f32 v84, v178, v179
	v_cvt_pk_bf16_f32 v85, v180, v181
	v_cvt_pk_bf16_f32 v86, v182, v183
	v_cvt_pk_bf16_f32 v87, v184, v185
	v_sub_f32_e32 v186, v186, v94
	v_sub_f32_e32 v187, v187, v94
	v_sub_f32_e32 v188, v188, v94
	v_sub_f32_e32 v189, v189, v94
	v_sub_f32_e32 v190, v190, v94
	v_sub_f32_e32 v191, v191, v94
	v_sub_f32_e32 v192, v192, v94
	v_sub_f32_e32 v193, v193, v94
	v_mfma_f32_32x32x16_bf16 v[34:49], v[138:141], v[84:87], v[34:49]
	v_mfma_f32_32x32x16_bf16 v[50:65], v[154:157], v[84:87], v[50:65]
	v_exp_f32_e32 v186, v186
	v_exp_f32_e32 v187, v187
	v_exp_f32_e32 v188, v188
	v_exp_f32_e32 v189, v189
	v_exp_f32_e32 v190, v190
	v_exp_f32_e32 v191, v191
	v_exp_f32_e32 v192, v192
	v_exp_f32_e32 v193, v193
	v_add_f32_e32 v238, v186, v187
	v_add_f32_e32 v238, v238, v188
	v_add_f32_e32 v238, v238, v189
	v_add_f32_e32 v238, v238, v190
	v_add_f32_e32 v238, v238, v191
	v_add_f32_e32 v238, v238, v192
	v_add_f32_e32 v238, v238, v193
	v_cvt_pk_bf16_f32 v88, v186, v187
	v_cvt_pk_bf16_f32 v89, v188, v189
	v_cvt_pk_bf16_f32 v90, v190, v191
	v_cvt_pk_bf16_f32 v91, v192, v193
	s_nop 1
	v_mfma_f32_32x32x16_bf16 v[34:49], v[142:145], v[88:91], v[34:49]
	v_mfma_f32_32x32x16_bf16 v[50:65], v[158:161], v[88:91], v[50:65]
	v_add_f32_e32 v235, v235, v236
	v_add_f32_e32 v237, v237, v238
	v_add_f32_e32 v235, v235, v237
	v_add_f32_e32 v66, v66, v235
	s_branch .Lw_next
.Lw_near:
	v_sub_u32_e32 v240, v232, v226
	v_lshl_add_u32 v240, v240, 2, v225
	s_waitcnt vmcnt(8) lgkmcnt(3)
	v_mfma_f32_32x32x16_bf16 v[162:177], v[98:101], v[68:71], 0
	v_mfma_f32_32x32x16_bf16 v[178:193], v[114:117], v[68:71], 0
	s_waitcnt lgkmcnt(2)
	v_mfma_f32_32x32x16_bf16 v[162:177], v[102:105], v[72:75], v[162:177]
	v_mfma_f32_32x32x16_bf16 v[178:193], v[118:121], v[72:75], v[178:193]
	s_waitcnt lgkmcnt(1)
	v_mfma_f32_32x32x16_bf16 v[162:177], v[106:109], v[76:79], v[162:177]
	v_mfma_f32_32x32x16_bf16 v[178:193], v[122:125], v[76:79], v[178:193]
	s_waitcnt lgkmcnt(0)
	v_mfma_f32_32x32x16_bf16 v[162:177], v[110:113], v[80:83], v[162:177]
	v_mfma_f32_32x32x16_bf16 v[178:193], v[126:129], v[80:83], v[178:193]
	ds_read2_b32 v[2:3], v240 offset0:64 offset1:63
	ds_read2_b32 v[4:5], v240 offset0:62 offset1:61
	ds_read2_b32 v[6:7], v240 offset0:56 offset1:55
	ds_read2_b32 v[8:9], v240 offset0:54 offset1:53
	ds_read2_b32 v[10:11], v240 offset0:48 offset1:47
	ds_read2_b32 v[12:13], v240 offset0:46 offset1:45
	ds_read2_b32 v[14:15], v240 offset0:40 offset1:39
	ds_read2_b32 v[16:17], v240 offset0:38 offset1:37
	ds_read2_b32 v[18:19], v240 offset0:32 offset1:31
	ds_read2_b32 v[20:21], v240 offset0:30 offset1:29
	ds_read2_b32 v[22:23], v240 offset0:24 offset1:23
	ds_read2_b32 v[24:25], v240 offset0:22 offset1:21
	ds_read2_b32 v[26:27], v240 offset0:16 offset1:15
	ds_read2_b32 v[28:29], v240 offset0:14 offset1:13
	ds_read2_b32 v[30:31], v240 offset0:8 offset1:7
	ds_read2_b32 v[32:33], v240 offset0:6 offset1:5
	s_cmp_lt_i32 s17, s44
	s_cbranch_scc0 .Lw_near_last
	s_add_u32 s22, s18, 0x2000
	s_addc_u32 s23, s19, 0
	global_load_dwordx4 v[98:101], v194, s[22:23]
	global_load_dwordx4 v[102:105], v194, s[22:23] offset:1024
	global_load_dwordx4 v[106:109], v194, s[22:23] offset:2048
	global_load_dwordx4 v[110:113], v194, s[22:23] offset:3072
	global_load_dwordx4 v[114:117], v200, s[22:23]
	global_load_dwordx4 v[118:121], v202, s[22:23]
	global_load_dwordx4 v[122:125], v204, s[22:23]
	global_load_dwordx4 v[126:129], v206, s[22:23]
.Lw_near_last:
	s_waitcnt lgkmcnt(8)
	v_fmamk_f32 v162, v162, 0x3fb8aa3b, v2
	v_fmamk_f32 v163, v163, 0x3fb8aa3b, v3
	v_fmamk_f32 v164, v164, 0x3fb8aa3b, v4
	v_fmamk_f32 v165, v165, 0x3fb8aa3b, v5
	v_fmamk_f32 v166, v166, 0x3fb8aa3b, v6
	v_fmamk_f32 v167, v167, 0x3fb8aa3b, v7
	v_fmamk_f32 v168, v168, 0x3fb8aa3b, v8
	v_fmamk_f32 v169, v169, 0x3fb8aa3b, v9
	v_fmamk_f32 v170, v170, 0x3fb8aa3b, v10
	v_fmamk_f32 v171, v171, 0x3fb8aa3b, v11
	v_fmamk_f32 v172, v172, 0x3fb8aa3b, v12
	v_fmamk_f32 v173, v173, 0x3fb8aa3b, v13
	v_fmamk_f32 v174, v174, 0x3fb8aa3b, v14
	v_fmamk_f32 v175, v175, 0x3fb8aa3b, v15
	v_fmamk_f32 v176, v176, 0x3fb8aa3b, v16
	v_fmamk_f32 v177, v177, 0x3fb8aa3b, v17
	s_waitcnt lgkmcnt(0)
	v_fmamk_f32 v178, v178, 0x3fb8aa3b, v18
	v_fmamk_f32 v179, v179, 0x3fb8aa3b, v19
	v_fmamk_f32 v180, v180, 0x3fb8aa3b, v20
	v_fmamk_f32 v181, v181, 0x3fb8aa3b, v21
	v_fmamk_f32 v182, v182, 0x3fb8aa3b, v22
	v_fmamk_f32 v183, v183, 0x3fb8aa3b, v23
	v_fmamk_f32 v184, v184, 0x3fb8aa3b, v24
	v_fmamk_f32 v185, v185, 0x3fb8aa3b, v25
	v_fmamk_f32 v186, v186, 0x3fb8aa3b, v26
	v_fmamk_f32 v187, v187, 0x3fb8aa3b, v27
	v_fmamk_f32 v188, v188, 0x3fb8aa3b, v28
	v_fmamk_f32 v189, v189, 0x3fb8aa3b, v29
	v_fmamk_f32 v190, v190, 0x3fb8aa3b, v30
	v_fmamk_f32 v191, v191, 0x3fb8aa3b, v31
	v_fmamk_f32 v192, v192, 0x3fb8aa3b, v32
	v_fmamk_f32 v193, v193, 0x3fb8aa3b, v33
	v_max3_f32 v92, v162, v163, v164
	v_max3_f32 v92, v92, v165, v166
	v_max3_f32 v92, v92, v167, v168
	v_max3_f32 v92, v92, v169, v170
	v_max3_f32 v92, v92, v171, v172
	v_max3_f32 v92, v92, v173, v174
	v_max3_f32 v92, v92, v175, v176
	v_max3_f32 v92, v92, v177, v177
	v_max3_f32 v96, v178, v179, v180
	v_max3_f32 v96, v96, v181, v182
	v_max3_f32 v96, v96, v183, v184
	v_max3_f32 v96, v96, v185, v186
	v_max3_f32 v96, v96, v187, v188
	v_max3_f32 v96, v96, v189, v190
	v_max3_f32 v96, v96, v191, v192
	v_max3_f32 v96, v96, v193, v193
	v_max_f32_e32 v92, v92, v96
	v_mov_b32_e32 v93, v92
	s_nop 1
	v_permlane32_swap_b32_e32 v92, v93
	v_max3_f32 v96, v234, v92, v93
	v_cmp_neq_f32_e32 vcc, s68, v96
	s_nop 1
	v_cndmask_b32_e32 v94, 0, v96, vcc
	v_cmp_neq_f32_e32 vcc, v96, v234
	s_cbranch_vccz .Lw_nr_near
	v_sub_f32_e32 v97, v234, v94
	v_exp_f32_e32 v97, v97
	s_nop 0
	v_mul_f32_e32 v34, v97, v34
	v_mul_f32_e32 v35, v97, v35
	v_mul_f32_e32 v36, v97, v36
	v_mul_f32_e32 v37, v97, v37
	v_mul_f32_e32 v38, v97, v38
	v_mul_f32_e32 v39, v97, v39
	v_mul_f32_e32 v40, v97, v40
	v_mul_f32_e32 v41, v97, v41
	v_mul_f32_e32 v42, v97, v42
	v_mul_f32_e32 v43, v97, v43
	v_mul_f32_e32 v44, v97, v44
	v_mul_f32_e32 v45, v97, v45
	v_mul_f32_e32 v46, v97, v46
	v_mul_f32_e32 v47, v97, v47
	v_mul_f32_e32 v48, v97, v48
	v_mul_f32_e32 v49, v97, v49
	v_mul_f32_e32 v50, v97, v50
	v_mul_f32_e32 v51, v97, v51
	v_mul_f32_e32 v52, v97, v52
	v_mul_f32_e32 v53, v97, v53
	v_mul_f32_e32 v54, v97, v54
	v_mul_f32_e32 v55, v97, v55
	v_mul_f32_e32 v56, v97, v56
	v_mul_f32_e32 v57, v97, v57
	v_mul_f32_e32 v58, v97, v58
	v_mul_f32_e32 v59, v97, v59
	v_mul_f32_e32 v60, v97, v60
	v_mul_f32_e32 v61, v97, v61
	v_mul_f32_e32 v62, v97, v62
	v_mul_f32_e32 v63, v97, v63
	v_mul_f32_e32 v64, v97, v64
	v_mul_f32_e32 v65, v97, v65
	v_mul_f32_e32 v66, v97, v66
.Lw_nr_near:
	v_mov_b32_e32 v234, v96
	v_sub_f32_e32 v162, v162, v94
	v_sub_f32_e32 v163, v163, v94
	v_sub_f32_e32 v164, v164, v94
	v_sub_f32_e32 v165, v165, v94
	v_sub_f32_e32 v166, v166, v94
	v_sub_f32_e32 v167, v167, v94
	v_sub_f32_e32 v168, v168, v94
	v_sub_f32_e32 v169, v169, v94
	v_exp_f32_e32 v162, v162
	v_exp_f32_e32 v163, v163
	v_exp_f32_e32 v164, v164
	v_exp_f32_e32 v165, v165
	v_exp_f32_e32 v166, v166
	v_exp_f32_e32 v167, v167
	v_exp_f32_e32 v168, v168
	v_exp_f32_e32 v169, v169
	v_add_f32_e32 v235, v162, v163
	v_add_f32_e32 v235, v235, v164
	v_add_f32_e32 v235, v235, v165
	v_add_f32_e32 v235, v235, v166
	v_add_f32_e32 v235, v235, v167
	v_add_f32_e32 v235, v235, v168
	v_add_f32_e32 v235, v235, v169
	v_cvt_pk_bf16_f32 v84, v162, v163
	v_cvt_pk_bf16_f32 v85, v164, v165
	v_cvt_pk_bf16_f32 v86, v166, v167
	v_cvt_pk_bf16_f32 v87, v168, v169
	v_sub_f32_e32 v170, v170, v94
	v_sub_f32_e32 v171, v171, v94
	v_sub_f32_e32 v172, v172, v94
	v_sub_f32_e32 v173, v173, v94
	v_sub_f32_e32 v174, v174, v94
	v_sub_f32_e32 v175, v175, v94
	v_sub_f32_e32 v176, v176, v94
	v_sub_f32_e32 v177, v177, v94
	s_cmp_lt_i32 s17, s44
	s_cbranch_scc1 .Lw_near_w8
	s_waitcnt vmcnt(0)
	s_branch .Lw_near_pv
.Lw_near_w8:
	s_waitcnt vmcnt(8)
.Lw_near_pv:
	v_mfma_f32_32x32x16_bf16 v[34:49], v[130:133], v[84:87], v[34:49]
	v_mfma_f32_32x32x16_bf16 v[50:65], v[146:149], v[84:87], v[50:65]
	v_exp_f32_e32 v170, v170
	v_exp_f32_e32 v171, v171
	v_exp_f32_e32 v172, v172
	v_exp_f32_e32 v173, v173
	v_exp_f32_e32 v174, v174
	v_exp_f32_e32 v175, v175
	v_exp_f32_e32 v176, v176
	v_exp_f32_e32 v177, v177
	v_add_f32_e32 v236, v170, v171
	v_add_f32_e32 v236, v236, v172
	v_add_f32_e32 v236, v236, v173
	v_add_f32_e32 v236, v236, v174
	v_add_f32_e32 v236, v236, v175
	v_add_f32_e32 v236, v236, v176
	v_add_f32_e32 v236, v236, v177
	v_cvt_pk_bf16_f32 v88, v170, v171
	v_cvt_pk_bf16_f32 v89, v172, v173
	v_cvt_pk_bf16_f32 v90, v174, v175
	v_cvt_pk_bf16_f32 v91, v176, v177
	v_sub_f32_e32 v178, v178, v94
	v_sub_f32_e32 v179, v179, v94
	v_sub_f32_e32 v180, v180, v94
	v_sub_f32_e32 v181, v181, v94
	v_sub_f32_e32 v182, v182, v94
	v_sub_f32_e32 v183, v183, v94
	v_sub_f32_e32 v184, v184, v94
	v_sub_f32_e32 v185, v185, v94
	v_mfma_f32_32x32x16_bf16 v[34:49], v[134:137], v[88:91], v[34:49]
	v_mfma_f32_32x32x16_bf16 v[50:65], v[150:153], v[88:91], v[50:65]
	v_exp_f32_e32 v178, v178
	v_exp_f32_e32 v179, v179
	v_exp_f32_e32 v180, v180
	v_exp_f32_e32 v181, v181
	v_exp_f32_e32 v182, v182
	v_exp_f32_e32 v183, v183
	v_exp_f32_e32 v184, v184
	v_exp_f32_e32 v185, v185
	v_add_f32_e32 v237, v178, v179
	v_add_f32_e32 v237, v237, v180
	v_add_f32_e32 v237, v237, v181
	v_add_f32_e32 v237, v237, v182
	v_add_f32_e32 v237, v237, v183
	v_add_f32_e32 v237, v237, v184
	v_add_f32_e32 v237, v237, v185
	v_cvt_pk_bf16_f32 v84, v178, v179
	v_cvt_pk_bf16_f32 v85, v180, v181
	v_cvt_pk_bf16_f32 v86, v182, v183
	v_cvt_pk_bf16_f32 v87, v184, v185
	v_sub_f32_e32 v186, v186, v94
	v_sub_f32_e32 v187, v187, v94
	v_sub_f32_e32 v188, v188, v94
	v_sub_f32_e32 v189, v189, v94
	v_sub_f32_e32 v190, v190, v94
	v_sub_f32_e32 v191, v191, v94
	v_sub_f32_e32 v192, v192, v94
	v_sub_f32_e32 v193, v193, v94
	v_mfma_f32_32x32x16_bf16 v[34:49], v[138:141], v[84:87], v[34:49]
	v_mfma_f32_32x32x16_bf16 v[50:65], v[154:157], v[84:87], v[50:65]
	v_exp_f32_e32 v186, v186
	v_exp_f32_e32 v187, v187
	v_exp_f32_e32 v188, v188
	v_exp_f32_e32 v189, v189
	v_exp_f32_e32 v190, v190
	v_exp_f32_e32 v191, v191
	v_exp_f32_e32 v192, v192
	v_exp_f32_e32 v193, v193
	v_add_f32_e32 v238, v186, v187
	v_add_f32_e32 v238, v238, v188
	v_add_f32_e32 v238, v238, v189
	v_add_f32_e32 v238, v238, v190
	v_add_f32_e32 v238, v238, v191
	v_add_f32_e32 v238, v238, v192
	v_add_f32_e32 v238, v238, v193
	v_cvt_pk_bf16_f32 v88, v186, v187
	v_cvt_pk_bf16_f32 v89, v188, v189
	v_cvt_pk_bf16_f32 v90, v190, v191
	v_cvt_pk_bf16_f32 v91, v192, v193
	s_nop 1
	v_mfma_f32_32x32x16_bf16 v[34:49], v[142:145], v[88:91], v[34:49]
	v_mfma_f32_32x32x16_bf16 v[50:65], v[158:161], v[88:91], v[50:65]
	v_add_f32_e32 v235, v235, v236
	v_add_f32_e32 v237, v237, v238
	v_add_f32_e32 v235, v235, v237
	v_add_f32_e32 v66, v66, v235
.Lw_next:
	v_subrev_u32_e32 v232, 64, v232
	s_add_u32 s18, s18, 0x2000
	s_addc_u32 s19, s19, 0
	s_add_i32 s17, s17, 1
	s_cmp_le_i32 s17, s44
	s_cbranch_scc1 .Lw_loop
